# epilogue trimming: the final s_waitcnt vmcnt(0) + s_barrier in front of s_endpgm removed
# baseline (speedup 1.0000x reference)
; #define PG8_WAIT_V(n) asm volatile("s_waitcnt vmcnt(" #n ")" ::: "memory")
; #define PG8_BAR __builtin_amdgcn_s_barrier()
; template <class Epi, class Sched, bool ALIGN_EPI = false, bool SP2 = false>
; __device__ __forceinline__ void gemm_phase(PG8_LAS unsigned char* lds, const Gemm g, const Sched& S, const Epi& E) {
;     ...
;     PG8_WAIT_V(0);
;     if constexpr (!ALIGN_EPI) { if (wr == 0) PG8_BAR; }
;     PG8_BAR;
.LBB0_591:
.LBB0_592:
	s_endpgm
